# layer-1 memory-cross-attention weight conversion shifted to waves 512-1023 (phase-0 per-wave item balance)
# speedup vs baseline: 1.0044x; 1.0044x over previous
; __global__ void __launch_bounds__(NTHREADS, 2) hybrid_fwd(Params P) {
;     ...
;             for (int l2 = 0; l2 < 2; ++l2) {
;                 conv_matrix(PL->in[I_MXWQ] + (size_t)l2 * DM * 512, DM, 512, PL->in[I_MXN] + l2 * DM, (bf16_t*)(ws + WS_WMQ) + (size_t)l2 * 512 * DM, DM, 0, 0, scr, lane, gw, NGW);
;                 conv_matrix(PL->in[I_MXWO] + (size_t)l2 * 512 * DM, 512, DM, nullptr, (bf16_t*)(ws + WS_WMO) + (size_t)l2 * DM * 512, 512, 0, 0, scr, lane, gw, NGW);
;             }
.LBB0_128:
	s_xor_b64 s[22:23], s[18:19], -1
	s_mov_b32 s5, 1
	s_mov_b64 s[18:19], 0
	s_and_b64 vcc, exec, s[22:23]
	s_cbranch_vccnz .LBB0_136
	s_add_i32 s4, s4, 0xfffffe00
	s_cmp_lt_u32 s4, 0x200
	s_cselect_b64 s[16:17], -1, 0

; __global__ void __launch_bounds__(NTHREADS, 2) hybrid_fwd(Params P) {
;     ...
;             for (int l2 = 0; l2 < 2; ++l2) {
;                 conv_matrix(PL->in[I_MXWQ] + (size_t)l2 * DM * 512, DM, 512, PL->in[I_MXN] + l2 * DM, (bf16_t*)(ws + WS_WMQ) + (size_t)l2 * 512 * DM, DM, 0, 0, scr, lane, gw, NGW);
;                 conv_matrix(PL->in[I_MXWO] + (size_t)l2 * 512 * DM, 512, DM, nullptr, (bf16_t*)(ws + WS_WMO) + (size_t)l2 * DM * 512, 512, 0, 0, scr, lane, gw, NGW);
;             }
;             conv_matrix(PL->in[I_MEMWKV], DM, 1024, PL->in[I_MEMN], (bf16_t*)(ws + WS_WMKV), DM, 0, 0, scr, lane, gw, NGW);
.LBB0_136:
	s_add_i32 s4, s4, 0x200
	s_sub_i32 s12, s8, s4
	s_add_i32 s12, s12, -1
	s_cmpk_gt_i32 s12, 0x3ff
	s_cbranch_scc1 .LBB0_141
	v_readlane_b32 s5, v254, 20
	s_mov_b64 s[16:17], 0xd800000
	v_lshl_add_u64 v[4:5], v[4:5], 0, s[16:17]
	v_mov_b32_e32 v6, s5
	v_readlane_b32 s5, v254, 21
	s_lshl_b32 s9, s8, 5
	v_mov_b32_e32 v7, s5
	ds_read_b64 v[8:9], v7
	ds_read_b64 v[6:7], v6
	s_lshl_b32 s5, s12, 5
	s_waitcnt lgkmcnt(0)
	v_lshl_add_u64 v[2:3], v[2:3], 2, v[8:9]
	v_cmp_ne_u64_e64 s[40:41], 0, v[6:7]
	s_branch .LBB0_139
